# late weight-transposition items at the P3 queue tail: next dequeue atomic issued at the start of the item (same prefetch mechanism as the attention units)
# speedup vs baseline: 1.0141x; 1.0022x over previous
; #define LAS __attribute__((address_space(3)))
; DI int transposes_total(bool late) { int total = 0; for (int s = 0; s < NSEG; ++s) if (seg_late(s) == late) total += (SEGS[s].K / 64) * ((SEGS[s].len + 31) / 32); return total; }
; DI void transpose_by_index(const Params& P, unsigned char* ws, LAS float* scr, int idx, bool late, int lane) {
;     int rem = idx, s = 0;
;     for (; s < NSEG; ++s) { if (seg_late(s) != late) continue; const int n = (SEGS[s].K / 64) * ((SEGS[s].len + 31) / 32); if (rem < n) break; rem -= n; }
;     const Seg sg = SEGS[s]; const int nnb = (sg.len + 31) / 32;
; __global__ void __launch_bounds__(512) fwd_kernel(Params P) {
;     ...
;             const int nlate = transposes_total(true), nlate_wg = (nlate + 7) >> 3;
;             if (u >= 128 + 2048 + nlate_wg) break;
;             if (u >= 128 + 2048) {
;                 const int idx = (u - (128 + 2048)) * 8 + wid;
;                 if (idx < nlate) transpose_by_index(P, ws, (LAS float*)(L + 40960 + wid * 8448), idx, true, lane);
.Lq_site2_skip:
	s_mov_b64 exec, s[0:1]
	s_mov_b32 s98, 1
	s_lshl_b32 s0, s7, 3
	v_readlane_b32 s1, v250, 9
	s_add_i32 s30, s1, s0
	v_readlane_b32 s0, v251, 56
	s_cmp_ge_i32 s30, s0
	s_cbranch_scc1 .LBB0_465
	s_cmp_lt_i32 s30, s64
	s_mov_b64 s[0:1], 11
	s_cbranch_scc1 .LBB0_647
	s_sub_i32 s30, s30, s64
	s_cmp_lt_i32 s30, s65
	s_mov_b64 s[0:1], 12
	s_cbranch_scc1 .LBB0_648
	s_sub_i32 s30, s30, s65
	s_cmp_lt_i32 s30, s74
	s_mov_b64 s[0:1], 13
	s_cbranch_scc1 .LBB0_649
	s_sub_i32 s30, s30, s74
	s_cmp_lt_i32 s30, s75
	s_mov_b64 s[0:1], 14
	s_cbranch_scc1 .LBB0_650
	s_sub_i32 s30, s30, s75
	s_cmp_lt_i32 s30, s81
	s_mov_b64 s[0:1], 15
	s_cbranch_scc1 .LBB0_651
	s_sub_i32 s30, s30, s81
	s_cmp_lt_i32 s30, s91
	s_mov_b64 s[0:1], 18
	s_cbranch_scc1 .LBB0_652
	s_sub_i32 s30, s30, s91
	s_cmp_lt_i32 s30, s92
	s_mov_b64 s[0:1], 19
	s_cbranch_scc1 .LBB0_653
	s_sub_i32 s30, s30, s92
	s_cmp_lt_i32 s30, s87
	s_mov_b64 s[0:1], 20
	s_cbranch_scc1 .LBB0_654
	s_sub_i32 s30, s30, s87
	s_cmp_lt_i32 s30, s88
	s_mov_b64 s[0:1], 21
	s_cbranch_scc1 .LBB0_655
	s_sub_i32 s30, s30, s88
	s_cmp_lt_i32 s30, s89
	s_mov_b64 s[0:1], 22
	s_cbranch_scc1 .LBB0_656
	s_sub_i32 s30, s30, s89
	s_mov_b64 s[0:1], 23
	v_readlane_b32 s7, v251, 55
	s_branch .LBB0_657
